# K-loop s_setprio flips removed (both GEMM loops and their peeled first iterations)
# speedup vs baseline: 1.0024x; 1.0024x over previous
.Lpl_out_j1:
	s_waitcnt lgkmcnt(0)
	s_barrier
	s_waitcnt lgkmcnt(0)
	v_mfma_f32_16x16x32_bf16 v[134:137], v[0:3], v[188:191], 0
	v_mfma_f32_16x16x32_bf16 v[130:133], v[138:141], v[188:191], 0
	v_mfma_f32_16x16x32_bf16 v[118:121], v[0:3], v[196:199], 0
	v_mfma_f32_16x16x32_bf16 v[114:117], v[138:141], v[196:199], 0
	v_mfma_f32_16x16x32_bf16 v[102:105], v[0:3], v[204:207], 0
	v_mfma_f32_16x16x32_bf16 v[98:101], v[138:141], v[204:207], 0
	v_mfma_f32_16x16x32_bf16 v[84:87], v[0:3], v[238:241], 0
	v_mfma_f32_16x16x32_bf16 v[80:83], v[138:141], v[238:241], 0
	v_mfma_f32_16x16x32_bf16 v[134:137], v[4:7], v[192:195], v[134:137]
	v_mfma_f32_16x16x32_bf16 v[130:133], v[142:145], v[192:195], v[130:133]
	v_mfma_f32_16x16x32_bf16 v[118:121], v[4:7], v[200:203], v[118:121]
	v_mfma_f32_16x16x32_bf16 v[114:117], v[142:145], v[200:203], v[114:117]
	v_mfma_f32_16x16x32_bf16 v[102:105], v[4:7], v[234:237], v[102:105]
	v_mfma_f32_16x16x32_bf16 v[98:101], v[142:145], v[234:237], v[98:101]
	v_mfma_f32_16x16x32_bf16 v[84:87], v[4:7], v[242:245], v[84:87]
	v_mfma_f32_16x16x32_bf16 v[80:83], v[142:145], v[242:245], v[80:83]
	v_mfma_f32_16x16x32_bf16 v[126:129], v[146:149], v[188:191], 0
	v_mfma_f32_16x16x32_bf16 v[122:125], v[180:183], v[188:191], 0
	v_mfma_f32_16x16x32_bf16 v[110:113], v[146:149], v[196:199], 0
	v_mfma_f32_16x16x32_bf16 v[106:109], v[180:183], v[196:199], 0
	v_mfma_f32_16x16x32_bf16 v[92:95], v[146:149], v[204:207], 0
	v_mfma_f32_16x16x32_bf16 v[88:91], v[180:183], v[204:207], 0
	v_mfma_f32_16x16x32_bf16 v[76:79], v[146:149], v[238:241], 0
	v_mfma_f32_16x16x32_bf16 v[72:75], v[180:183], v[238:241], 0
	v_mfma_f32_16x16x32_bf16 v[126:129], v[150:153], v[192:195], v[126:129]
	v_mfma_f32_16x16x32_bf16 v[122:125], v[184:187], v[192:195], v[122:125]
	v_mfma_f32_16x16x32_bf16 v[110:113], v[150:153], v[200:203], v[110:113]
	v_mfma_f32_16x16x32_bf16 v[106:109], v[184:187], v[200:203], v[106:109]
	v_mfma_f32_16x16x32_bf16 v[92:95], v[150:153], v[234:237], v[92:95]
	v_mfma_f32_16x16x32_bf16 v[88:91], v[184:187], v[234:237], v[88:91]
	v_mfma_f32_16x16x32_bf16 v[76:79], v[150:153], v[242:245], v[76:79]
	v_mfma_f32_16x16x32_bf16 v[72:75], v[184:187], v[242:245], v[72:75]
	s_barrier
	s_add_i32 s23, s23, s58
	v_lshl_add_u64 v[170:171], s[12:13], 0, v[156:157]
	s_mov_b32 m0, s23
	ds_read_b128 v[188:191], v231 offset:16384
	ds_read_b128 v[192:195], v231 offset:17408
	ds_read_b128 v[196:199], v231 offset:18432
	ds_read_b128 v[200:203], v231 offset:19456
	ds_read_b128 v[204:207], v231 offset:20480
	ds_read_b128 v[234:237], v231 offset:21504
	ds_read_b128 v[238:241], v231 offset:22528
	ds_read_b128 v[242:245], v231 offset:23552
	global_load_lds_dwordx4 v[170:171], off
	s_add_i32 m0, s23, 0x2000
	s_add_u32 s26, s12, 0x10000
	v_lshl_add_u64 v[208:209], s[12:13], 0, v[160:161]
	s_addc_u32 s27, s13, 0
	s_add_i32 s23, s31, s58
	global_load_lds_dwordx4 v[208:209], off
	v_lshl_add_u64 v[246:247], s[26:27], 0, v[156:157]
	s_mov_b32 m0, s23
	v_lshl_add_u64 v[248:249], s[14:15], 0, v[158:159]
	global_load_lds_dwordx4 v[246:247], off
	v_lshl_add_u64 v[246:247], s[26:27], 0, v[160:161]
	s_add_i32 m0, s23, 0x2000
	s_nop 0
	global_load_lds_dwordx4 v[246:247], off
	v_lshl_add_u64 v[246:247], s[14:15], 0, v[154:155]
	s_mov_b32 m0, s69
	s_nop 0
	global_load_lds_dwordx4 v[246:247], off
	s_mov_b32 m0, s70
	s_nop 0
	global_load_lds_dwordx4 v[248:249], off
	s_cmp_lg_u32 s100, 0
	s_cbranch_scc1 .Lpl_out_r2
	s_waitcnt vmcnt(8)
	s_branch .Lpl_out_j2

.Lpl_out_j2:
	s_mov_b32 s100, 0
	s_waitcnt lgkmcnt(0)
	s_barrier
	s_waitcnt lgkmcnt(0)
	v_mfma_f32_16x16x32_bf16 v[68:71], v[0:3], v[188:191], 0
	v_mfma_f32_16x16x32_bf16 v[64:67], v[138:141], v[188:191], 0
	v_mfma_f32_16x16x32_bf16 v[52:55], v[0:3], v[196:199], 0
	v_mfma_f32_16x16x32_bf16 v[48:51], v[138:141], v[196:199], 0
	v_mfma_f32_16x16x32_bf16 v[36:39], v[0:3], v[204:207], 0
	v_mfma_f32_16x16x32_bf16 v[32:35], v[138:141], v[204:207], 0
	v_mfma_f32_16x16x32_bf16 v[0:3], v[0:3], v[238:241], 0
	v_mfma_f32_16x16x32_bf16 v[68:71], v[4:7], v[192:195], v[68:71]
	v_mfma_f32_16x16x32_bf16 v[64:67], v[142:145], v[192:195], v[64:67]
	v_mfma_f32_16x16x32_bf16 v[52:55], v[4:7], v[200:203], v[52:55]
	v_mfma_f32_16x16x32_bf16 v[48:51], v[142:145], v[200:203], v[48:51]
	v_mfma_f32_16x16x32_bf16 v[36:39], v[4:7], v[234:237], v[36:39]
	v_mfma_f32_16x16x32_bf16 v[32:35], v[142:145], v[234:237], v[32:35]
	v_mfma_f32_16x16x32_bf16 v[0:3], v[4:7], v[242:245], v[0:3]
	v_mfma_f32_16x16x32_bf16 v[4:7], v[138:141], v[238:241], 0
	v_mfma_f32_16x16x32_bf16 v[4:7], v[142:145], v[242:245], v[4:7]
	v_mfma_f32_16x16x32_bf16 v[16:19], v[146:149], v[188:191], 0
	v_mfma_f32_16x16x32_bf16 v[60:63], v[150:153], v[192:195], v[16:19]
	v_mfma_f32_16x16x32_bf16 v[16:19], v[180:183], v[188:191], 0
	v_mfma_f32_16x16x32_bf16 v[56:59], v[184:187], v[192:195], v[16:19]
	v_mfma_f32_16x16x32_bf16 v[16:19], v[146:149], v[196:199], 0
	v_mfma_f32_16x16x32_bf16 v[44:47], v[150:153], v[200:203], v[16:19]
	v_mfma_f32_16x16x32_bf16 v[16:19], v[180:183], v[196:199], 0
	v_mfma_f32_16x16x32_bf16 v[40:43], v[184:187], v[200:203], v[16:19]
	v_mfma_f32_16x16x32_bf16 v[16:19], v[146:149], v[204:207], 0
	v_mfma_f32_16x16x32_bf16 v[28:31], v[150:153], v[234:237], v[16:19]
	v_mfma_f32_16x16x32_bf16 v[16:19], v[180:183], v[204:207], 0
	v_mfma_f32_16x16x32_bf16 v[12:15], v[146:149], v[238:241], 0
	v_mfma_f32_16x16x32_bf16 v[8:11], v[180:183], v[238:241], 0
	v_mfma_f32_16x16x32_bf16 v[24:27], v[184:187], v[234:237], v[16:19]
	v_mfma_f32_16x16x32_bf16 v[12:15], v[150:153], v[242:245], v[12:15]
	v_mfma_f32_16x16x32_bf16 v[8:11], v[184:187], v[242:245], v[8:11]
	s_barrier
	v_add_u32_e32 v96, s67, v221
	s_add_i32 s23, 0, 0x1c000
	ds_read_b128 v[16:19], v96
	ds_read_b128 v[20:23], v96 offset:1024
	ds_read_b128 v[138:141], v96 offset:2048
	ds_read_b128 v[142:145], v96 offset:3072
	v_add_u32_e32 v96, s23, v221
	ds_read_b128 v[146:149], v96
	ds_read_b128 v[150:153], v96 offset:1024
	ds_read_b128 v[180:183], v96 offset:2048
	ds_read_b128 v[184:187], v96 offset:3072
	s_add_u32 s14, s14, 0x40000
	s_addc_u32 s15, s15, 0
	s_mov_b32 m0, s71
	v_lshl_add_u64 v[250:251], s[14:15], 0, v[154:155]
	ds_read_b128 v[188:191], v231 offset:32768
	ds_read_b128 v[192:195], v231 offset:33792
	ds_read_b128 v[196:199], v231 offset:34816
	ds_read_b128 v[200:203], v231 offset:35840
	ds_read_b128 v[204:207], v231 offset:36864
	ds_read_b128 v[234:237], v231 offset:37888
	ds_read_b128 v[238:241], v231 offset:38912
	ds_read_b128 v[242:245], v231 offset:39936
	global_load_lds_dwordx4 v[250:251], off
	v_lshl_add_u64 v[250:251], s[14:15], 0, v[158:159]
	s_mov_b32 m0, s76
	s_nop 0
	global_load_lds_dwordx4 v[250:251], off
	s_waitcnt vmcnt(8)
	s_waitcnt lgkmcnt(0)
	s_barrier
	s_waitcnt lgkmcnt(0)
	v_mfma_f32_16x16x32_bf16 v[134:137], v[16:19], v[188:191], v[134:137]
	v_mfma_f32_16x16x32_bf16 v[130:133], v[138:141], v[188:191], v[130:133]
	v_mfma_f32_16x16x32_bf16 v[118:121], v[16:19], v[196:199], v[118:121]
	v_mfma_f32_16x16x32_bf16 v[114:117], v[138:141], v[196:199], v[114:117]
	v_mfma_f32_16x16x32_bf16 v[102:105], v[16:19], v[204:207], v[102:105]
	v_mfma_f32_16x16x32_bf16 v[98:101], v[138:141], v[204:207], v[98:101]
	v_mfma_f32_16x16x32_bf16 v[84:87], v[16:19], v[238:241], v[84:87]
	v_mfma_f32_16x16x32_bf16 v[80:83], v[138:141], v[238:241], v[80:83]
	v_mfma_f32_16x16x32_bf16 v[134:137], v[20:23], v[192:195], v[134:137]
	v_mfma_f32_16x16x32_bf16 v[130:133], v[142:145], v[192:195], v[130:133]
	v_mfma_f32_16x16x32_bf16 v[118:121], v[20:23], v[200:203], v[118:121]
	v_mfma_f32_16x16x32_bf16 v[114:117], v[142:145], v[200:203], v[114:117]
	v_mfma_f32_16x16x32_bf16 v[102:105], v[20:23], v[234:237], v[102:105]
	v_mfma_f32_16x16x32_bf16 v[98:101], v[142:145], v[234:237], v[98:101]
	v_mfma_f32_16x16x32_bf16 v[84:87], v[20:23], v[242:245], v[84:87]
	v_mfma_f32_16x16x32_bf16 v[80:83], v[142:145], v[242:245], v[80:83]
	v_mfma_f32_16x16x32_bf16 v[126:129], v[146:149], v[188:191], v[126:129]
	v_mfma_f32_16x16x32_bf16 v[122:125], v[180:183], v[188:191], v[122:125]
	v_mfma_f32_16x16x32_bf16 v[110:113], v[146:149], v[196:199], v[110:113]
	v_mfma_f32_16x16x32_bf16 v[106:109], v[180:183], v[196:199], v[106:109]
	v_mfma_f32_16x16x32_bf16 v[92:95], v[146:149], v[204:207], v[92:95]
	v_mfma_f32_16x16x32_bf16 v[88:91], v[180:183], v[204:207], v[88:91]
	v_mfma_f32_16x16x32_bf16 v[76:79], v[146:149], v[238:241], v[76:79]
	v_mfma_f32_16x16x32_bf16 v[72:75], v[180:183], v[238:241], v[72:75]
	v_mfma_f32_16x16x32_bf16 v[126:129], v[150:153], v[192:195], v[126:129]
	v_mfma_f32_16x16x32_bf16 v[122:125], v[184:187], v[192:195], v[122:125]
	v_mfma_f32_16x16x32_bf16 v[110:113], v[150:153], v[200:203], v[110:113]
	v_mfma_f32_16x16x32_bf16 v[106:109], v[184:187], v[200:203], v[106:109]
	v_mfma_f32_16x16x32_bf16 v[92:95], v[150:153], v[234:237], v[92:95]
	v_mfma_f32_16x16x32_bf16 v[88:91], v[184:187], v[234:237], v[88:91]
	v_mfma_f32_16x16x32_bf16 v[76:79], v[150:153], v[242:245], v[76:79]
	v_mfma_f32_16x16x32_bf16 v[72:75], v[184:187], v[242:245], v[72:75]
	s_barrier
	s_add_i32 s14, s67, s58
	v_lshl_add_u64 v[170:171], v[170:171], 0, s[62:63]
	s_mov_b32 m0, s14
	ds_read_b128 v[188:191], v231 offset:49152
	ds_read_b128 v[192:195], v231 offset:50176
	ds_read_b128 v[196:199], v231 offset:51200
	ds_read_b128 v[200:203], v231 offset:52224
	ds_read_b128 v[204:207], v231 offset:53248
	ds_read_b128 v[234:237], v231 offset:54272
	ds_read_b128 v[238:241], v231 offset:55296
	ds_read_b128 v[242:245], v231 offset:56320
	global_load_lds_dwordx4 v[170:171], off
	s_add_i32 m0, s14, 0x2000
	s_add_u32 s12, s12, 0x10080
	v_lshl_add_u64 v[170:171], v[208:209], 0, s[62:63]
	s_addc_u32 s13, s13, 0
	s_add_i32 s14, s23, s58
	global_load_lds_dwordx4 v[170:171], off
	v_lshl_add_u64 v[170:171], s[12:13], 0, v[156:157]
	s_mov_b32 m0, s14
	s_nop 0
	global_load_lds_dwordx4 v[170:171], off
	v_lshl_add_u64 v[170:171], s[12:13], 0, v[160:161]
	s_add_i32 m0, s14, 0x2000
	s_nop 0
	global_load_lds_dwordx4 v[170:171], off
	v_lshl_add_u64 v[170:171], v[246:247], 0, s[62:63]
	s_mov_b32 m0, s96
	s_nop 0
	global_load_lds_dwordx4 v[170:171], off
	v_lshl_add_u64 v[170:171], v[248:249], 0, s[62:63]
	s_mov_b32 m0, s36
	s_nop 0
	global_load_lds_dwordx4 v[170:171], off
	s_waitcnt vmcnt(8)
	s_waitcnt lgkmcnt(0)
	s_barrier
	s_waitcnt lgkmcnt(0)
	v_mfma_f32_16x16x32_bf16 v[68:71], v[16:19], v[188:191], v[68:71]
	v_mfma_f32_16x16x32_bf16 v[52:55], v[16:19], v[196:199], v[52:55]
	v_mfma_f32_16x16x32_bf16 v[36:39], v[16:19], v[204:207], v[36:39]
	v_mfma_f32_16x16x32_bf16 v[0:3], v[16:19], v[238:241], v[0:3]
	v_mfma_f32_16x16x32_bf16 v[68:71], v[20:23], v[192:195], v[68:71]
	v_mfma_f32_16x16x32_bf16 v[64:67], v[138:141], v[188:191], v[64:67]
	v_mfma_f32_16x16x32_bf16 v[52:55], v[20:23], v[200:203], v[52:55]
	v_mfma_f32_16x16x32_bf16 v[48:51], v[138:141], v[196:199], v[48:51]
	v_mfma_f32_16x16x32_bf16 v[36:39], v[20:23], v[234:237], v[36:39]
	v_mfma_f32_16x16x32_bf16 v[32:35], v[138:141], v[204:207], v[32:35]
	v_mfma_f32_16x16x32_bf16 v[20:23], v[20:23], v[242:245], v[0:3]
	v_mfma_f32_16x16x32_bf16 v[0:3], v[138:141], v[238:241], v[4:7]
	v_mfma_f32_16x16x32_bf16 v[64:67], v[142:145], v[192:195], v[64:67]
	v_mfma_f32_16x16x32_bf16 v[48:51], v[142:145], v[200:203], v[48:51]
	v_mfma_f32_16x16x32_bf16 v[32:35], v[142:145], v[234:237], v[32:35]
	v_mfma_f32_16x16x32_bf16 v[16:19], v[142:145], v[242:245], v[0:3]
	v_mfma_f32_16x16x32_bf16 v[0:3], v[146:149], v[188:191], v[60:63]
	v_mfma_f32_16x16x32_bf16 v[60:63], v[150:153], v[192:195], v[0:3]
	v_mfma_f32_16x16x32_bf16 v[0:3], v[180:183], v[188:191], v[56:59]
	v_mfma_f32_16x16x32_bf16 v[56:59], v[184:187], v[192:195], v[0:3]
	v_mfma_f32_16x16x32_bf16 v[0:3], v[146:149], v[196:199], v[44:47]
	v_mfma_f32_16x16x32_bf16 v[44:47], v[150:153], v[200:203], v[0:3]
	v_mfma_f32_16x16x32_bf16 v[0:3], v[180:183], v[196:199], v[40:43]
	v_mfma_f32_16x16x32_bf16 v[40:43], v[184:187], v[200:203], v[0:3]
	v_mfma_f32_16x16x32_bf16 v[0:3], v[146:149], v[204:207], v[28:31]
	v_mfma_f32_16x16x32_bf16 v[28:31], v[150:153], v[234:237], v[0:3]
	v_mfma_f32_16x16x32_bf16 v[0:3], v[180:183], v[204:207], v[24:27]
	v_mfma_f32_16x16x32_bf16 v[24:27], v[184:187], v[234:237], v[0:3]
	v_mfma_f32_16x16x32_bf16 v[0:3], v[146:149], v[238:241], v[12:15]
	v_mfma_f32_16x16x32_bf16 v[12:15], v[150:153], v[242:245], v[0:3]
	v_mfma_f32_16x16x32_bf16 v[0:3], v[180:183], v[238:241], v[8:11]
	v_mfma_f32_16x16x32_bf16 v[8:11], v[184:187], v[242:245], v[0:3]
	s_barrier
	s_add_i32 s22, s22, 2
	s_add_u32 s2, s2, 0x100
	s_addc_u32 s3, s3, 0
	s_add_u32 s20, s20, 0x100
	s_addc_u32 s21, s21, 0
	.p2align 6
.LBB0_405:
	s_add_u32 s12, s2, 0xfffc0080
	s_addc_u32 s13, s3, -1
	s_add_i32 s23, 0, 0x10000
	s_cmp_eq_u32 s22, 12
	s_cselect_b32 s15, s16, s13
	s_cselect_b32 s14, s17, s12
	v_add_u32_e32 v96, s23, v221
	s_cselect_b32 s13, s18, s21
	s_cselect_b32 s12, s19, s20
	s_add_i32 s31, 0, 0x14000
	ds_read_b128 v[0:3], v96
	ds_read_b128 v[4:7], v96 offset:1024
	ds_read_b128 v[138:141], v96 offset:2048
	ds_read_b128 v[142:145], v96 offset:3072
	v_add_u32_e32 v96, s31, v221
	ds_read_b128 v[146:149], v96
	ds_read_b128 v[150:153], v96 offset:1024
	ds_read_b128 v[180:183], v96 offset:2048
	ds_read_b128 v[184:187], v96 offset:3072
	v_lshl_add_u64 v[170:171], s[2:3], 0, v[166:167]
	s_add_i32 m0, s69, 0xc000
	ds_read_b128 v[188:191], v231
	ds_read_b128 v[192:195], v231 offset:1024
	ds_read_b128 v[196:199], v231 offset:2048
	ds_read_b128 v[200:203], v231 offset:3072
	ds_read_b128 v[204:207], v231 offset:4096
	ds_read_b128 v[234:237], v231 offset:5120
	ds_read_b128 v[238:241], v231 offset:6144
	ds_read_b128 v[242:245], v231 offset:7168
	global_load_lds_dwordx4 v[170:171], off
	v_lshl_add_u64 v[170:171], s[2:3], 0, v[168:169]
	s_add_i32 m0, s69, 0xe000
	s_nop 0
	global_load_lds_dwordx4 v[170:171], off
	s_waitcnt vmcnt(8)
	s_waitcnt lgkmcnt(0)
	s_barrier
	s_waitcnt lgkmcnt(0)
	v_mfma_f32_16x16x32_bf16 v[134:137], v[0:3], v[188:191], v[134:137]
	v_mfma_f32_16x16x32_bf16 v[130:133], v[138:141], v[188:191], v[130:133]
	v_mfma_f32_16x16x32_bf16 v[118:121], v[0:3], v[196:199], v[118:121]
	v_mfma_f32_16x16x32_bf16 v[114:117], v[138:141], v[196:199], v[114:117]
	v_mfma_f32_16x16x32_bf16 v[102:105], v[0:3], v[204:207], v[102:105]
	v_mfma_f32_16x16x32_bf16 v[98:101], v[138:141], v[204:207], v[98:101]
	v_mfma_f32_16x16x32_bf16 v[84:87], v[0:3], v[238:241], v[84:87]
	v_mfma_f32_16x16x32_bf16 v[80:83], v[138:141], v[238:241], v[80:83]
	v_mfma_f32_16x16x32_bf16 v[134:137], v[4:7], v[192:195], v[134:137]
	v_mfma_f32_16x16x32_bf16 v[130:133], v[142:145], v[192:195], v[130:133]
	v_mfma_f32_16x16x32_bf16 v[118:121], v[4:7], v[200:203], v[118:121]
	v_mfma_f32_16x16x32_bf16 v[114:117], v[142:145], v[200:203], v[114:117]
	v_mfma_f32_16x16x32_bf16 v[102:105], v[4:7], v[234:237], v[102:105]
	v_mfma_f32_16x16x32_bf16 v[98:101], v[142:145], v[234:237], v[98:101]
	v_mfma_f32_16x16x32_bf16 v[84:87], v[4:7], v[242:245], v[84:87]
	v_mfma_f32_16x16x32_bf16 v[80:83], v[142:145], v[242:245], v[80:83]
	v_mfma_f32_16x16x32_bf16 v[126:129], v[146:149], v[188:191], v[126:129]
	v_mfma_f32_16x16x32_bf16 v[122:125], v[180:183], v[188:191], v[122:125]
	v_mfma_f32_16x16x32_bf16 v[110:113], v[146:149], v[196:199], v[110:113]
	v_mfma_f32_16x16x32_bf16 v[106:109], v[180:183], v[196:199], v[106:109]
	v_mfma_f32_16x16x32_bf16 v[92:95], v[146:149], v[204:207], v[92:95]
	v_mfma_f32_16x16x32_bf16 v[88:91], v[180:183], v[204:207], v[88:91]
	v_mfma_f32_16x16x32_bf16 v[76:79], v[146:149], v[238:241], v[76:79]
	v_mfma_f32_16x16x32_bf16 v[72:75], v[180:183], v[238:241], v[72:75]
	v_mfma_f32_16x16x32_bf16 v[126:129], v[150:153], v[192:195], v[126:129]
	v_mfma_f32_16x16x32_bf16 v[122:125], v[184:187], v[192:195], v[122:125]
	v_mfma_f32_16x16x32_bf16 v[110:113], v[150:153], v[200:203], v[110:113]
	v_mfma_f32_16x16x32_bf16 v[106:109], v[184:187], v[200:203], v[106:109]
	v_mfma_f32_16x16x32_bf16 v[92:95], v[150:153], v[234:237], v[92:95]
	v_mfma_f32_16x16x32_bf16 v[88:91], v[184:187], v[234:237], v[88:91]
	v_mfma_f32_16x16x32_bf16 v[76:79], v[150:153], v[242:245], v[76:79]
	v_mfma_f32_16x16x32_bf16 v[72:75], v[184:187], v[242:245], v[72:75]
	s_barrier
	s_add_i32 s23, s23, s58
	v_lshl_add_u64 v[170:171], s[12:13], 0, v[156:157]
	s_mov_b32 m0, s23
	ds_read_b128 v[188:191], v231 offset:16384
	ds_read_b128 v[192:195], v231 offset:17408
	ds_read_b128 v[196:199], v231 offset:18432
	ds_read_b128 v[200:203], v231 offset:19456
	ds_read_b128 v[204:207], v231 offset:20480
	ds_read_b128 v[234:237], v231 offset:21504
	ds_read_b128 v[238:241], v231 offset:22528
	ds_read_b128 v[242:245], v231 offset:23552
	global_load_lds_dwordx4 v[170:171], off
	s_add_i32 m0, s23, 0x2000
	s_add_u32 s26, s12, 0x10000
	v_lshl_add_u64 v[208:209], s[12:13], 0, v[160:161]
	s_addc_u32 s27, s13, 0
	s_add_i32 s23, s31, s58
	global_load_lds_dwordx4 v[208:209], off
	v_lshl_add_u64 v[246:247], s[26:27], 0, v[156:157]
	s_mov_b32 m0, s23
	v_lshl_add_u64 v[248:249], s[14:15], 0, v[158:159]
	global_load_lds_dwordx4 v[246:247], off
	v_lshl_add_u64 v[246:247], s[26:27], 0, v[160:161]
	s_add_i32 m0, s23, 0x2000
	s_nop 0
	global_load_lds_dwordx4 v[246:247], off
	v_lshl_add_u64 v[246:247], s[14:15], 0, v[154:155]
	s_mov_b32 m0, s69
	s_nop 0
	global_load_lds_dwordx4 v[246:247], off
	s_mov_b32 m0, s70
	s_nop 0
	global_load_lds_dwordx4 v[248:249], off
	s_waitcnt vmcnt(8)
	s_waitcnt lgkmcnt(0)
	s_barrier
	s_waitcnt lgkmcnt(0)
	v_mfma_f32_16x16x32_bf16 v[68:71], v[0:3], v[188:191], v[68:71]
	v_mfma_f32_16x16x32_bf16 v[64:67], v[138:141], v[188:191], v[64:67]
	v_mfma_f32_16x16x32_bf16 v[52:55], v[0:3], v[196:199], v[52:55]
	v_mfma_f32_16x16x32_bf16 v[48:51], v[138:141], v[196:199], v[48:51]
	v_mfma_f32_16x16x32_bf16 v[36:39], v[0:3], v[204:207], v[36:39]
	v_mfma_f32_16x16x32_bf16 v[32:35], v[138:141], v[204:207], v[32:35]
	v_mfma_f32_16x16x32_bf16 v[0:3], v[0:3], v[238:241], v[20:23]
	v_mfma_f32_16x16x32_bf16 v[68:71], v[4:7], v[192:195], v[68:71]
	v_mfma_f32_16x16x32_bf16 v[64:67], v[142:145], v[192:195], v[64:67]
	v_mfma_f32_16x16x32_bf16 v[52:55], v[4:7], v[200:203], v[52:55]
	v_mfma_f32_16x16x32_bf16 v[48:51], v[142:145], v[200:203], v[48:51]
	v_mfma_f32_16x16x32_bf16 v[36:39], v[4:7], v[234:237], v[36:39]
	v_mfma_f32_16x16x32_bf16 v[32:35], v[142:145], v[234:237], v[32:35]
	v_mfma_f32_16x16x32_bf16 v[0:3], v[4:7], v[242:245], v[0:3]
	v_mfma_f32_16x16x32_bf16 v[4:7], v[138:141], v[238:241], v[16:19]
	v_mfma_f32_16x16x32_bf16 v[4:7], v[142:145], v[242:245], v[4:7]
	v_mfma_f32_16x16x32_bf16 v[16:19], v[146:149], v[188:191], v[60:63]
	v_mfma_f32_16x16x32_bf16 v[60:63], v[150:153], v[192:195], v[16:19]
	v_mfma_f32_16x16x32_bf16 v[16:19], v[180:183], v[188:191], v[56:59]
	v_mfma_f32_16x16x32_bf16 v[56:59], v[184:187], v[192:195], v[16:19]
	v_mfma_f32_16x16x32_bf16 v[16:19], v[146:149], v[196:199], v[44:47]
	v_mfma_f32_16x16x32_bf16 v[44:47], v[150:153], v[200:203], v[16:19]
	v_mfma_f32_16x16x32_bf16 v[16:19], v[180:183], v[196:199], v[40:43]
	v_mfma_f32_16x16x32_bf16 v[40:43], v[184:187], v[200:203], v[16:19]
	v_mfma_f32_16x16x32_bf16 v[16:19], v[146:149], v[204:207], v[28:31]
	v_mfma_f32_16x16x32_bf16 v[28:31], v[150:153], v[234:237], v[16:19]
	v_mfma_f32_16x16x32_bf16 v[16:19], v[180:183], v[204:207], v[24:27]
	v_mfma_f32_16x16x32_bf16 v[12:15], v[146:149], v[238:241], v[12:15]
	v_mfma_f32_16x16x32_bf16 v[8:11], v[180:183], v[238:241], v[8:11]
	v_mfma_f32_16x16x32_bf16 v[24:27], v[184:187], v[234:237], v[16:19]
	v_mfma_f32_16x16x32_bf16 v[12:15], v[150:153], v[242:245], v[12:15]
	v_mfma_f32_16x16x32_bf16 v[8:11], v[184:187], v[242:245], v[8:11]
	s_barrier
	v_add_u32_e32 v96, s67, v221
	s_add_i32 s23, 0, 0x1c000
	ds_read_b128 v[16:19], v96
	ds_read_b128 v[20:23], v96 offset:1024
	ds_read_b128 v[138:141], v96 offset:2048
	ds_read_b128 v[142:145], v96 offset:3072
	v_add_u32_e32 v96, s23, v221
	ds_read_b128 v[146:149], v96
	ds_read_b128 v[150:153], v96 offset:1024
	ds_read_b128 v[180:183], v96 offset:2048
	ds_read_b128 v[184:187], v96 offset:3072
	s_add_u32 s14, s14, 0x40000
	s_addc_u32 s15, s15, 0
	s_mov_b32 m0, s71
	v_lshl_add_u64 v[250:251], s[14:15], 0, v[154:155]
	ds_read_b128 v[188:191], v231 offset:32768
	ds_read_b128 v[192:195], v231 offset:33792
	ds_read_b128 v[196:199], v231 offset:34816
	ds_read_b128 v[200:203], v231 offset:35840
	ds_read_b128 v[204:207], v231 offset:36864
	ds_read_b128 v[234:237], v231 offset:37888
	ds_read_b128 v[238:241], v231 offset:38912
	ds_read_b128 v[242:245], v231 offset:39936
	global_load_lds_dwordx4 v[250:251], off
	v_lshl_add_u64 v[250:251], s[14:15], 0, v[158:159]
	s_mov_b32 m0, s76
	s_nop 0
	global_load_lds_dwordx4 v[250:251], off
	s_waitcnt vmcnt(8)
	s_waitcnt lgkmcnt(0)
	s_barrier
	s_waitcnt lgkmcnt(0)
	v_mfma_f32_16x16x32_bf16 v[134:137], v[16:19], v[188:191], v[134:137]
	v_mfma_f32_16x16x32_bf16 v[130:133], v[138:141], v[188:191], v[130:133]
	v_mfma_f32_16x16x32_bf16 v[118:121], v[16:19], v[196:199], v[118:121]
	v_mfma_f32_16x16x32_bf16 v[114:117], v[138:141], v[196:199], v[114:117]
	v_mfma_f32_16x16x32_bf16 v[102:105], v[16:19], v[204:207], v[102:105]
	v_mfma_f32_16x16x32_bf16 v[98:101], v[138:141], v[204:207], v[98:101]
	v_mfma_f32_16x16x32_bf16 v[84:87], v[16:19], v[238:241], v[84:87]
	v_mfma_f32_16x16x32_bf16 v[80:83], v[138:141], v[238:241], v[80:83]
	v_mfma_f32_16x16x32_bf16 v[134:137], v[20:23], v[192:195], v[134:137]
	v_mfma_f32_16x16x32_bf16 v[130:133], v[142:145], v[192:195], v[130:133]
	v_mfma_f32_16x16x32_bf16 v[118:121], v[20:23], v[200:203], v[118:121]
	v_mfma_f32_16x16x32_bf16 v[114:117], v[142:145], v[200:203], v[114:117]
	v_mfma_f32_16x16x32_bf16 v[102:105], v[20:23], v[234:237], v[102:105]
	v_mfma_f32_16x16x32_bf16 v[98:101], v[142:145], v[234:237], v[98:101]
	v_mfma_f32_16x16x32_bf16 v[84:87], v[20:23], v[242:245], v[84:87]
	v_mfma_f32_16x16x32_bf16 v[80:83], v[142:145], v[242:245], v[80:83]
	v_mfma_f32_16x16x32_bf16 v[126:129], v[146:149], v[188:191], v[126:129]
	v_mfma_f32_16x16x32_bf16 v[122:125], v[180:183], v[188:191], v[122:125]
	v_mfma_f32_16x16x32_bf16 v[110:113], v[146:149], v[196:199], v[110:113]
	v_mfma_f32_16x16x32_bf16 v[106:109], v[180:183], v[196:199], v[106:109]
	v_mfma_f32_16x16x32_bf16 v[92:95], v[146:149], v[204:207], v[92:95]
	v_mfma_f32_16x16x32_bf16 v[88:91], v[180:183], v[204:207], v[88:91]
	v_mfma_f32_16x16x32_bf16 v[76:79], v[146:149], v[238:241], v[76:79]
	v_mfma_f32_16x16x32_bf16 v[72:75], v[180:183], v[238:241], v[72:75]
	v_mfma_f32_16x16x32_bf16 v[126:129], v[150:153], v[192:195], v[126:129]
	v_mfma_f32_16x16x32_bf16 v[122:125], v[184:187], v[192:195], v[122:125]
	v_mfma_f32_16x16x32_bf16 v[110:113], v[150:153], v[200:203], v[110:113]
	v_mfma_f32_16x16x32_bf16 v[106:109], v[184:187], v[200:203], v[106:109]
	v_mfma_f32_16x16x32_bf16 v[92:95], v[150:153], v[234:237], v[92:95]
	v_mfma_f32_16x16x32_bf16 v[88:91], v[184:187], v[234:237], v[88:91]
	v_mfma_f32_16x16x32_bf16 v[76:79], v[150:153], v[242:245], v[76:79]
	v_mfma_f32_16x16x32_bf16 v[72:75], v[184:187], v[242:245], v[72:75]
	s_barrier
	s_add_i32 s14, s67, s58
	v_lshl_add_u64 v[170:171], v[170:171], 0, s[62:63]
	s_mov_b32 m0, s14
	ds_read_b128 v[188:191], v231 offset:49152
	ds_read_b128 v[192:195], v231 offset:50176
	ds_read_b128 v[196:199], v231 offset:51200
	ds_read_b128 v[200:203], v231 offset:52224
	ds_read_b128 v[204:207], v231 offset:53248
	ds_read_b128 v[234:237], v231 offset:54272
	ds_read_b128 v[238:241], v231 offset:55296
	ds_read_b128 v[242:245], v231 offset:56320
	global_load_lds_dwordx4 v[170:171], off
	s_add_i32 m0, s14, 0x2000
	s_add_u32 s12, s12, 0x10080
	v_lshl_add_u64 v[170:171], v[208:209], 0, s[62:63]
	s_addc_u32 s13, s13, 0
	s_add_i32 s14, s23, s58
	global_load_lds_dwordx4 v[170:171], off
	v_lshl_add_u64 v[170:171], s[12:13], 0, v[156:157]
	s_mov_b32 m0, s14
	s_nop 0
	global_load_lds_dwordx4 v[170:171], off
	v_lshl_add_u64 v[170:171], s[12:13], 0, v[160:161]
	s_add_i32 m0, s14, 0x2000
	s_nop 0
	global_load_lds_dwordx4 v[170:171], off
	v_lshl_add_u64 v[170:171], v[246:247], 0, s[62:63]
	s_mov_b32 m0, s96
	s_nop 0
	global_load_lds_dwordx4 v[170:171], off
	v_lshl_add_u64 v[170:171], v[248:249], 0, s[62:63]
	s_mov_b32 m0, s36
	s_nop 0
	global_load_lds_dwordx4 v[170:171], off
	s_waitcnt vmcnt(8)
	s_waitcnt lgkmcnt(0)
	s_barrier
	s_waitcnt lgkmcnt(0)
	v_mfma_f32_16x16x32_bf16 v[68:71], v[16:19], v[188:191], v[68:71]
	v_mfma_f32_16x16x32_bf16 v[52:55], v[16:19], v[196:199], v[52:55]
	v_mfma_f32_16x16x32_bf16 v[36:39], v[16:19], v[204:207], v[36:39]
	v_mfma_f32_16x16x32_bf16 v[0:3], v[16:19], v[238:241], v[0:3]
	v_mfma_f32_16x16x32_bf16 v[68:71], v[20:23], v[192:195], v[68:71]
	v_mfma_f32_16x16x32_bf16 v[64:67], v[138:141], v[188:191], v[64:67]
	v_mfma_f32_16x16x32_bf16 v[52:55], v[20:23], v[200:203], v[52:55]
	v_mfma_f32_16x16x32_bf16 v[48:51], v[138:141], v[196:199], v[48:51]
	v_mfma_f32_16x16x32_bf16 v[36:39], v[20:23], v[234:237], v[36:39]
	v_mfma_f32_16x16x32_bf16 v[32:35], v[138:141], v[204:207], v[32:35]
	v_mfma_f32_16x16x32_bf16 v[20:23], v[20:23], v[242:245], v[0:3]
	v_mfma_f32_16x16x32_bf16 v[0:3], v[138:141], v[238:241], v[4:7]
	v_mfma_f32_16x16x32_bf16 v[64:67], v[142:145], v[192:195], v[64:67]
	v_mfma_f32_16x16x32_bf16 v[48:51], v[142:145], v[200:203], v[48:51]
	v_mfma_f32_16x16x32_bf16 v[32:35], v[142:145], v[234:237], v[32:35]
	v_mfma_f32_16x16x32_bf16 v[16:19], v[142:145], v[242:245], v[0:3]
	v_mfma_f32_16x16x32_bf16 v[0:3], v[146:149], v[188:191], v[60:63]
	v_mfma_f32_16x16x32_bf16 v[60:63], v[150:153], v[192:195], v[0:3]
	v_mfma_f32_16x16x32_bf16 v[0:3], v[180:183], v[188:191], v[56:59]
	v_mfma_f32_16x16x32_bf16 v[56:59], v[184:187], v[192:195], v[0:3]
	v_mfma_f32_16x16x32_bf16 v[0:3], v[146:149], v[196:199], v[44:47]
	v_mfma_f32_16x16x32_bf16 v[44:47], v[150:153], v[200:203], v[0:3]
	v_mfma_f32_16x16x32_bf16 v[0:3], v[180:183], v[196:199], v[40:43]
	v_mfma_f32_16x16x32_bf16 v[40:43], v[184:187], v[200:203], v[0:3]
	v_mfma_f32_16x16x32_bf16 v[0:3], v[146:149], v[204:207], v[28:31]
	v_mfma_f32_16x16x32_bf16 v[28:31], v[150:153], v[234:237], v[0:3]
	v_mfma_f32_16x16x32_bf16 v[0:3], v[180:183], v[204:207], v[24:27]
	v_mfma_f32_16x16x32_bf16 v[24:27], v[184:187], v[234:237], v[0:3]
	v_mfma_f32_16x16x32_bf16 v[0:3], v[146:149], v[238:241], v[12:15]
	v_mfma_f32_16x16x32_bf16 v[12:15], v[150:153], v[242:245], v[0:3]
	v_mfma_f32_16x16x32_bf16 v[0:3], v[180:183], v[238:241], v[8:11]
	v_mfma_f32_16x16x32_bf16 v[8:11], v[184:187], v[242:245], v[0:3]
	s_barrier
	s_add_i32 s22, s22, 2
	s_add_u32 s2, s2, 0x100
	s_addc_u32 s3, s3, 0
	s_add_u32 s20, s20, 0x100
	s_addc_u32 s21, s21, 0
	s_cmp_gt_u32 s22, 13
	s_cbranch_scc0 .LBB0_405
	s_and_b64 vcc, exec, s[42:43]
	s_cbranch_vccz .LBB0_418
	s_barrier
	s_andn2_b64 vcc, exec, s[38:39]
	s_mov_b64 s[2:3], -1
	s_cbranch_vccz .LBB0_419

.Lpl_in_j1:
	s_waitcnt lgkmcnt(0)
	s_barrier
	s_waitcnt lgkmcnt(0)
	v_mfma_f32_16x16x32_bf16 v[134:137], v[0:3], v[190:193], 0
	v_mfma_f32_16x16x32_bf16 v[130:133], v[138:141], v[190:193], 0
	v_mfma_f32_16x16x32_bf16 v[118:121], v[0:3], v[198:201], 0
	v_mfma_f32_16x16x32_bf16 v[114:117], v[138:141], v[198:201], 0
	v_mfma_f32_16x16x32_bf16 v[102:105], v[0:3], v[222:225], 0
	v_mfma_f32_16x16x32_bf16 v[98:101], v[138:141], v[222:225], 0
	v_mfma_f32_16x16x32_bf16 v[84:87], v[0:3], v[230:233], 0
	v_mfma_f32_16x16x32_bf16 v[80:83], v[138:141], v[230:233], 0
	v_mfma_f32_16x16x32_bf16 v[134:137], v[4:7], v[194:197], v[134:137]
	v_mfma_f32_16x16x32_bf16 v[130:133], v[142:145], v[194:197], v[130:133]
	v_mfma_f32_16x16x32_bf16 v[118:121], v[4:7], v[202:205], v[118:121]
	v_mfma_f32_16x16x32_bf16 v[114:117], v[142:145], v[202:205], v[114:117]
	v_mfma_f32_16x16x32_bf16 v[102:105], v[4:7], v[226:229], v[102:105]
	v_mfma_f32_16x16x32_bf16 v[98:101], v[142:145], v[226:229], v[98:101]
	v_mfma_f32_16x16x32_bf16 v[84:87], v[4:7], v[234:237], v[84:87]
	v_mfma_f32_16x16x32_bf16 v[80:83], v[142:145], v[234:237], v[80:83]
	v_mfma_f32_16x16x32_bf16 v[126:129], v[146:149], v[190:193], 0
	v_mfma_f32_16x16x32_bf16 v[122:125], v[182:185], v[190:193], 0
	v_mfma_f32_16x16x32_bf16 v[110:113], v[146:149], v[198:201], 0
	v_mfma_f32_16x16x32_bf16 v[106:109], v[182:185], v[198:201], 0
	v_mfma_f32_16x16x32_bf16 v[92:95], v[146:149], v[222:225], 0
	v_mfma_f32_16x16x32_bf16 v[88:91], v[182:185], v[222:225], 0
	v_mfma_f32_16x16x32_bf16 v[76:79], v[146:149], v[230:233], 0
	v_mfma_f32_16x16x32_bf16 v[72:75], v[182:185], v[230:233], 0
	v_mfma_f32_16x16x32_bf16 v[126:129], v[150:153], v[194:197], v[126:129]
	v_mfma_f32_16x16x32_bf16 v[122:125], v[186:189], v[194:197], v[122:125]
	v_mfma_f32_16x16x32_bf16 v[110:113], v[150:153], v[202:205], v[110:113]
	v_mfma_f32_16x16x32_bf16 v[106:109], v[186:189], v[202:205], v[106:109]
	v_mfma_f32_16x16x32_bf16 v[92:95], v[150:153], v[226:229], v[92:95]
	v_mfma_f32_16x16x32_bf16 v[88:91], v[186:189], v[226:229], v[88:91]
	v_mfma_f32_16x16x32_bf16 v[76:79], v[150:153], v[234:237], v[76:79]
	v_mfma_f32_16x16x32_bf16 v[72:75], v[186:189], v[234:237], v[72:75]
	s_barrier
	s_add_i32 s33, s33, s78
	v_lshl_add_u64 v[238:239], s[12:13], 0, v[156:157]
	s_mov_b32 m0, s33
	ds_read_b128 v[190:193], v221 offset:16384
	ds_read_b128 v[194:197], v221 offset:17408
	ds_read_b128 v[198:201], v221 offset:18432
	ds_read_b128 v[202:205], v221 offset:19456
	ds_read_b128 v[222:225], v221 offset:20480
	ds_read_b128 v[226:229], v221 offset:21504
	ds_read_b128 v[230:233], v221 offset:22528
	ds_read_b128 v[234:237], v221 offset:23552
	global_load_lds_dwordx4 v[238:239], off
	s_add_i32 m0, s33, 0x2000
	s_add_u32 s42, s12, 0x10000
	v_lshl_add_u64 v[240:241], s[12:13], 0, v[160:161]
	s_addc_u32 s43, s13, 0
	s_add_i32 s33, s35, s78
	global_load_lds_dwordx4 v[240:241], off
	v_lshl_add_u64 v[242:243], s[42:43], 0, v[156:157]
	s_mov_b32 m0, s33
	v_lshl_add_u64 v[244:245], s[14:15], 0, v[158:159]
	global_load_lds_dwordx4 v[242:243], off
	v_lshl_add_u64 v[242:243], s[42:43], 0, v[160:161]
	s_add_i32 m0, s33, 0x2000
	s_nop 0
	global_load_lds_dwordx4 v[242:243], off
	v_lshl_add_u64 v[242:243], s[14:15], 0, v[154:155]
	s_mov_b32 m0, s79
	s_nop 0
	global_load_lds_dwordx4 v[242:243], off
	s_mov_b32 m0, s81
	s_nop 0
	global_load_lds_dwordx4 v[244:245], off
	s_cmp_lg_u32 s100, 0
	s_cbranch_scc1 .Lpl_in_r2
	s_waitcnt vmcnt(8)
	s_branch .Lpl_in_j2

.Lpl_in_j2:
	s_mov_b32 s100, 0
	s_waitcnt lgkmcnt(0)
	s_barrier
	s_waitcnt lgkmcnt(0)
	v_mfma_f32_16x16x32_bf16 v[68:71], v[0:3], v[190:193], 0
	v_mfma_f32_16x16x32_bf16 v[64:67], v[138:141], v[190:193], 0
	v_mfma_f32_16x16x32_bf16 v[52:55], v[0:3], v[198:201], 0
	v_mfma_f32_16x16x32_bf16 v[48:51], v[138:141], v[198:201], 0
	v_mfma_f32_16x16x32_bf16 v[36:39], v[0:3], v[222:225], 0
	v_mfma_f32_16x16x32_bf16 v[32:35], v[138:141], v[222:225], 0
	v_mfma_f32_16x16x32_bf16 v[0:3], v[0:3], v[230:233], 0
	v_mfma_f32_16x16x32_bf16 v[68:71], v[4:7], v[194:197], v[68:71]
	v_mfma_f32_16x16x32_bf16 v[64:67], v[142:145], v[194:197], v[64:67]
	v_mfma_f32_16x16x32_bf16 v[52:55], v[4:7], v[202:205], v[52:55]
	v_mfma_f32_16x16x32_bf16 v[48:51], v[142:145], v[202:205], v[48:51]
	v_mfma_f32_16x16x32_bf16 v[36:39], v[4:7], v[226:229], v[36:39]
	v_mfma_f32_16x16x32_bf16 v[32:35], v[142:145], v[226:229], v[32:35]
	v_mfma_f32_16x16x32_bf16 v[0:3], v[4:7], v[234:237], v[0:3]
	v_mfma_f32_16x16x32_bf16 v[4:7], v[138:141], v[230:233], 0
	v_mfma_f32_16x16x32_bf16 v[4:7], v[142:145], v[234:237], v[4:7]
	v_mfma_f32_16x16x32_bf16 v[16:19], v[146:149], v[190:193], 0
	v_mfma_f32_16x16x32_bf16 v[60:63], v[150:153], v[194:197], v[16:19]
	v_mfma_f32_16x16x32_bf16 v[16:19], v[182:185], v[190:193], 0
	v_mfma_f32_16x16x32_bf16 v[56:59], v[186:189], v[194:197], v[16:19]
	v_mfma_f32_16x16x32_bf16 v[16:19], v[146:149], v[198:201], 0
	v_mfma_f32_16x16x32_bf16 v[44:47], v[150:153], v[202:205], v[16:19]
	v_mfma_f32_16x16x32_bf16 v[16:19], v[182:185], v[198:201], 0
	v_mfma_f32_16x16x32_bf16 v[40:43], v[186:189], v[202:205], v[16:19]
	v_mfma_f32_16x16x32_bf16 v[16:19], v[146:149], v[222:225], 0
	v_mfma_f32_16x16x32_bf16 v[28:31], v[150:153], v[226:229], v[16:19]
	v_mfma_f32_16x16x32_bf16 v[16:19], v[182:185], v[222:225], 0
	v_mfma_f32_16x16x32_bf16 v[12:15], v[146:149], v[230:233], 0
	v_mfma_f32_16x16x32_bf16 v[8:11], v[182:185], v[230:233], 0
	v_mfma_f32_16x16x32_bf16 v[24:27], v[186:189], v[226:229], v[16:19]
	v_mfma_f32_16x16x32_bf16 v[12:15], v[150:153], v[234:237], v[12:15]
	v_mfma_f32_16x16x32_bf16 v[8:11], v[186:189], v[234:237], v[8:11]
	s_barrier
	v_add_u32_e32 v96, s67, v165
	s_add_i32 s33, 0, 0x1c000
	ds_read_b128 v[16:19], v96
	ds_read_b128 v[20:23], v96 offset:1024
	ds_read_b128 v[138:141], v96 offset:2048
	ds_read_b128 v[142:145], v96 offset:3072
	v_add_u32_e32 v96, s33, v165
	ds_read_b128 v[146:149], v96
	ds_read_b128 v[150:153], v96 offset:1024
	ds_read_b128 v[182:185], v96 offset:2048
	ds_read_b128 v[186:189], v96 offset:3072
	s_add_u32 s14, s14, 0x40000
	s_addc_u32 s15, s15, 0
	s_mov_b32 m0, s92
	v_lshl_add_u64 v[246:247], s[14:15], 0, v[154:155]
	ds_read_b128 v[190:193], v221 offset:32768
	ds_read_b128 v[194:197], v221 offset:33792
	ds_read_b128 v[198:201], v221 offset:34816
	ds_read_b128 v[202:205], v221 offset:35840
	ds_read_b128 v[222:225], v221 offset:36864
	ds_read_b128 v[226:229], v221 offset:37888
	ds_read_b128 v[230:233], v221 offset:38912
	ds_read_b128 v[234:237], v221 offset:39936
	global_load_lds_dwordx4 v[246:247], off
	v_lshl_add_u64 v[246:247], s[14:15], 0, v[158:159]
	s_mov_b32 m0, s93
	s_nop 0
	global_load_lds_dwordx4 v[246:247], off
	s_waitcnt vmcnt(8)
	s_waitcnt lgkmcnt(0)
	s_barrier
	s_waitcnt lgkmcnt(0)
	v_mfma_f32_16x16x32_bf16 v[134:137], v[16:19], v[190:193], v[134:137]
	v_mfma_f32_16x16x32_bf16 v[130:133], v[138:141], v[190:193], v[130:133]
	v_mfma_f32_16x16x32_bf16 v[118:121], v[16:19], v[198:201], v[118:121]
	v_mfma_f32_16x16x32_bf16 v[114:117], v[138:141], v[198:201], v[114:117]
	v_mfma_f32_16x16x32_bf16 v[102:105], v[16:19], v[222:225], v[102:105]
	v_mfma_f32_16x16x32_bf16 v[98:101], v[138:141], v[222:225], v[98:101]
	v_mfma_f32_16x16x32_bf16 v[84:87], v[16:19], v[230:233], v[84:87]
	v_mfma_f32_16x16x32_bf16 v[80:83], v[138:141], v[230:233], v[80:83]
	v_mfma_f32_16x16x32_bf16 v[134:137], v[20:23], v[194:197], v[134:137]
	v_mfma_f32_16x16x32_bf16 v[130:133], v[142:145], v[194:197], v[130:133]
	v_mfma_f32_16x16x32_bf16 v[118:121], v[20:23], v[202:205], v[118:121]
	v_mfma_f32_16x16x32_bf16 v[114:117], v[142:145], v[202:205], v[114:117]
	v_mfma_f32_16x16x32_bf16 v[102:105], v[20:23], v[226:229], v[102:105]
	v_mfma_f32_16x16x32_bf16 v[98:101], v[142:145], v[226:229], v[98:101]
	v_mfma_f32_16x16x32_bf16 v[84:87], v[20:23], v[234:237], v[84:87]
	v_mfma_f32_16x16x32_bf16 v[80:83], v[142:145], v[234:237], v[80:83]
	v_mfma_f32_16x16x32_bf16 v[126:129], v[146:149], v[190:193], v[126:129]
	v_mfma_f32_16x16x32_bf16 v[122:125], v[182:185], v[190:193], v[122:125]
	v_mfma_f32_16x16x32_bf16 v[110:113], v[146:149], v[198:201], v[110:113]
	v_mfma_f32_16x16x32_bf16 v[106:109], v[182:185], v[198:201], v[106:109]
	v_mfma_f32_16x16x32_bf16 v[92:95], v[146:149], v[222:225], v[92:95]
	v_mfma_f32_16x16x32_bf16 v[88:91], v[182:185], v[222:225], v[88:91]
	v_mfma_f32_16x16x32_bf16 v[76:79], v[146:149], v[230:233], v[76:79]
	v_mfma_f32_16x16x32_bf16 v[72:75], v[182:185], v[230:233], v[72:75]
	v_mfma_f32_16x16x32_bf16 v[126:129], v[150:153], v[194:197], v[126:129]
	v_mfma_f32_16x16x32_bf16 v[122:125], v[186:189], v[194:197], v[122:125]
	v_mfma_f32_16x16x32_bf16 v[110:113], v[150:153], v[202:205], v[110:113]
	v_mfma_f32_16x16x32_bf16 v[106:109], v[186:189], v[202:205], v[106:109]
	v_mfma_f32_16x16x32_bf16 v[92:95], v[150:153], v[226:229], v[92:95]
	v_mfma_f32_16x16x32_bf16 v[88:91], v[186:189], v[226:229], v[88:91]
	v_mfma_f32_16x16x32_bf16 v[76:79], v[150:153], v[234:237], v[76:79]
	v_mfma_f32_16x16x32_bf16 v[72:75], v[186:189], v[234:237], v[72:75]
	s_barrier
	s_add_i32 s14, s67, s78
	v_lshl_add_u64 v[238:239], v[238:239], 0, s[62:63]
	s_mov_b32 m0, s14
	ds_read_b128 v[190:193], v221 offset:49152
	ds_read_b128 v[194:197], v221 offset:50176
	ds_read_b128 v[198:201], v221 offset:51200
	ds_read_b128 v[202:205], v221 offset:52224
	ds_read_b128 v[222:225], v221 offset:53248
	ds_read_b128 v[226:229], v221 offset:54272
	ds_read_b128 v[230:233], v221 offset:55296
	ds_read_b128 v[234:237], v221 offset:56320
	global_load_lds_dwordx4 v[238:239], off
	s_add_i32 m0, s14, 0x2000
	s_add_u32 s12, s12, 0x10080
	v_lshl_add_u64 v[238:239], v[240:241], 0, s[62:63]
	s_addc_u32 s13, s13, 0
	s_add_i32 s14, s33, s78
	global_load_lds_dwordx4 v[238:239], off
	v_lshl_add_u64 v[238:239], s[12:13], 0, v[156:157]
	s_mov_b32 m0, s14
	s_nop 0
	global_load_lds_dwordx4 v[238:239], off
	v_lshl_add_u64 v[238:239], s[12:13], 0, v[160:161]
	s_add_i32 m0, s14, 0x2000
	s_nop 0
	global_load_lds_dwordx4 v[238:239], off
	v_lshl_add_u64 v[238:239], v[242:243], 0, s[62:63]
	s_mov_b32 m0, s21
	s_nop 0
	global_load_lds_dwordx4 v[238:239], off
	v_lshl_add_u64 v[238:239], v[244:245], 0, s[62:63]
	s_mov_b32 m0, s61
	s_nop 0
	global_load_lds_dwordx4 v[238:239], off
	s_waitcnt vmcnt(8)
	s_waitcnt lgkmcnt(0)
	s_barrier
	s_waitcnt lgkmcnt(0)
	v_mfma_f32_16x16x32_bf16 v[68:71], v[16:19], v[190:193], v[68:71]
	v_mfma_f32_16x16x32_bf16 v[52:55], v[16:19], v[198:201], v[52:55]
	v_mfma_f32_16x16x32_bf16 v[36:39], v[16:19], v[222:225], v[36:39]
	v_mfma_f32_16x16x32_bf16 v[0:3], v[16:19], v[230:233], v[0:3]
	v_mfma_f32_16x16x32_bf16 v[68:71], v[20:23], v[194:197], v[68:71]
	v_mfma_f32_16x16x32_bf16 v[64:67], v[138:141], v[190:193], v[64:67]
	v_mfma_f32_16x16x32_bf16 v[52:55], v[20:23], v[202:205], v[52:55]
	v_mfma_f32_16x16x32_bf16 v[48:51], v[138:141], v[198:201], v[48:51]
	v_mfma_f32_16x16x32_bf16 v[36:39], v[20:23], v[226:229], v[36:39]
	v_mfma_f32_16x16x32_bf16 v[32:35], v[138:141], v[222:225], v[32:35]
	v_mfma_f32_16x16x32_bf16 v[20:23], v[20:23], v[234:237], v[0:3]
	v_mfma_f32_16x16x32_bf16 v[0:3], v[138:141], v[230:233], v[4:7]
	v_mfma_f32_16x16x32_bf16 v[64:67], v[142:145], v[194:197], v[64:67]
	v_mfma_f32_16x16x32_bf16 v[48:51], v[142:145], v[202:205], v[48:51]
	v_mfma_f32_16x16x32_bf16 v[32:35], v[142:145], v[226:229], v[32:35]
	v_mfma_f32_16x16x32_bf16 v[16:19], v[142:145], v[234:237], v[0:3]
	v_mfma_f32_16x16x32_bf16 v[0:3], v[146:149], v[190:193], v[60:63]
	v_mfma_f32_16x16x32_bf16 v[60:63], v[150:153], v[194:197], v[0:3]
	v_mfma_f32_16x16x32_bf16 v[0:3], v[182:185], v[190:193], v[56:59]
	v_mfma_f32_16x16x32_bf16 v[56:59], v[186:189], v[194:197], v[0:3]
	v_mfma_f32_16x16x32_bf16 v[0:3], v[146:149], v[198:201], v[44:47]
	v_mfma_f32_16x16x32_bf16 v[44:47], v[150:153], v[202:205], v[0:3]
	v_mfma_f32_16x16x32_bf16 v[0:3], v[182:185], v[198:201], v[40:43]
	v_mfma_f32_16x16x32_bf16 v[40:43], v[186:189], v[202:205], v[0:3]
	v_mfma_f32_16x16x32_bf16 v[0:3], v[146:149], v[222:225], v[28:31]
	v_mfma_f32_16x16x32_bf16 v[28:31], v[150:153], v[226:229], v[0:3]
	v_mfma_f32_16x16x32_bf16 v[0:3], v[182:185], v[222:225], v[24:27]
	v_mfma_f32_16x16x32_bf16 v[24:27], v[186:189], v[226:229], v[0:3]
	v_mfma_f32_16x16x32_bf16 v[0:3], v[146:149], v[230:233], v[12:15]
	v_mfma_f32_16x16x32_bf16 v[12:15], v[150:153], v[234:237], v[0:3]
	v_mfma_f32_16x16x32_bf16 v[0:3], v[182:185], v[230:233], v[8:11]
	v_mfma_f32_16x16x32_bf16 v[8:11], v[186:189], v[234:237], v[0:3]
	s_barrier
	s_add_i32 s27, s27, 2
	s_add_u32 s4, s4, 0x100
	s_addc_u32 s5, s5, 0
	s_add_u32 s19, s19, 0x100
	s_addc_u32 s26, s26, 0
	.p2align 6
.LBB0_750:
	s_add_u32 s12, s4, 0xfffc0080
	s_addc_u32 s13, s5, -1
	s_add_i32 s33, 0, 0x10000
	s_cmp_eq_u32 s27, 12
	s_cselect_b32 s15, s3, s13
	s_cselect_b32 s14, s16, s12
	v_add_u32_e32 v96, s33, v165
	s_cselect_b32 s13, s17, s26
	s_cselect_b32 s12, s18, s19
	s_add_i32 s35, 0, 0x14000
	ds_read_b128 v[0:3], v96
	ds_read_b128 v[4:7], v96 offset:1024
	ds_read_b128 v[138:141], v96 offset:2048
	ds_read_b128 v[142:145], v96 offset:3072
	v_add_u32_e32 v96, s35, v165
	ds_read_b128 v[146:149], v96
	ds_read_b128 v[150:153], v96 offset:1024
	ds_read_b128 v[182:185], v96 offset:2048
	ds_read_b128 v[186:189], v96 offset:3072
	v_lshl_add_u64 v[238:239], s[4:5], 0, v[168:169]
	s_add_i32 m0, s79, 0xc000
	ds_read_b128 v[190:193], v221
	ds_read_b128 v[194:197], v221 offset:1024
	ds_read_b128 v[198:201], v221 offset:2048
	ds_read_b128 v[202:205], v221 offset:3072
	ds_read_b128 v[222:225], v221 offset:4096
	ds_read_b128 v[226:229], v221 offset:5120
	ds_read_b128 v[230:233], v221 offset:6144
	ds_read_b128 v[234:237], v221 offset:7168
	global_load_lds_dwordx4 v[238:239], off
	v_lshl_add_u64 v[238:239], s[4:5], 0, v[170:171]
	s_add_i32 m0, s79, 0xe000
	s_nop 0
	global_load_lds_dwordx4 v[238:239], off
	s_waitcnt vmcnt(8)
	s_waitcnt lgkmcnt(0)
	s_barrier
	s_waitcnt lgkmcnt(0)
	v_mfma_f32_16x16x32_bf16 v[134:137], v[0:3], v[190:193], v[134:137]
	v_mfma_f32_16x16x32_bf16 v[130:133], v[138:141], v[190:193], v[130:133]
	v_mfma_f32_16x16x32_bf16 v[118:121], v[0:3], v[198:201], v[118:121]
	v_mfma_f32_16x16x32_bf16 v[114:117], v[138:141], v[198:201], v[114:117]
	v_mfma_f32_16x16x32_bf16 v[102:105], v[0:3], v[222:225], v[102:105]
	v_mfma_f32_16x16x32_bf16 v[98:101], v[138:141], v[222:225], v[98:101]
	v_mfma_f32_16x16x32_bf16 v[84:87], v[0:3], v[230:233], v[84:87]
	v_mfma_f32_16x16x32_bf16 v[80:83], v[138:141], v[230:233], v[80:83]
	v_mfma_f32_16x16x32_bf16 v[134:137], v[4:7], v[194:197], v[134:137]
	v_mfma_f32_16x16x32_bf16 v[130:133], v[142:145], v[194:197], v[130:133]
	v_mfma_f32_16x16x32_bf16 v[118:121], v[4:7], v[202:205], v[118:121]
	v_mfma_f32_16x16x32_bf16 v[114:117], v[142:145], v[202:205], v[114:117]
	v_mfma_f32_16x16x32_bf16 v[102:105], v[4:7], v[226:229], v[102:105]
	v_mfma_f32_16x16x32_bf16 v[98:101], v[142:145], v[226:229], v[98:101]
	v_mfma_f32_16x16x32_bf16 v[84:87], v[4:7], v[234:237], v[84:87]
	v_mfma_f32_16x16x32_bf16 v[80:83], v[142:145], v[234:237], v[80:83]
	v_mfma_f32_16x16x32_bf16 v[126:129], v[146:149], v[190:193], v[126:129]
	v_mfma_f32_16x16x32_bf16 v[122:125], v[182:185], v[190:193], v[122:125]
	v_mfma_f32_16x16x32_bf16 v[110:113], v[146:149], v[198:201], v[110:113]
	v_mfma_f32_16x16x32_bf16 v[106:109], v[182:185], v[198:201], v[106:109]
	v_mfma_f32_16x16x32_bf16 v[92:95], v[146:149], v[222:225], v[92:95]
	v_mfma_f32_16x16x32_bf16 v[88:91], v[182:185], v[222:225], v[88:91]
	v_mfma_f32_16x16x32_bf16 v[76:79], v[146:149], v[230:233], v[76:79]
	v_mfma_f32_16x16x32_bf16 v[72:75], v[182:185], v[230:233], v[72:75]
	v_mfma_f32_16x16x32_bf16 v[126:129], v[150:153], v[194:197], v[126:129]
	v_mfma_f32_16x16x32_bf16 v[122:125], v[186:189], v[194:197], v[122:125]
	v_mfma_f32_16x16x32_bf16 v[110:113], v[150:153], v[202:205], v[110:113]
	v_mfma_f32_16x16x32_bf16 v[106:109], v[186:189], v[202:205], v[106:109]
	v_mfma_f32_16x16x32_bf16 v[92:95], v[150:153], v[226:229], v[92:95]
	v_mfma_f32_16x16x32_bf16 v[88:91], v[186:189], v[226:229], v[88:91]
	v_mfma_f32_16x16x32_bf16 v[76:79], v[150:153], v[234:237], v[76:79]
	v_mfma_f32_16x16x32_bf16 v[72:75], v[186:189], v[234:237], v[72:75]
	s_barrier
	s_add_i32 s33, s33, s78
	v_lshl_add_u64 v[238:239], s[12:13], 0, v[156:157]
	s_mov_b32 m0, s33
	ds_read_b128 v[190:193], v221 offset:16384
	ds_read_b128 v[194:197], v221 offset:17408
	ds_read_b128 v[198:201], v221 offset:18432
	ds_read_b128 v[202:205], v221 offset:19456
	ds_read_b128 v[222:225], v221 offset:20480
	ds_read_b128 v[226:229], v221 offset:21504
	ds_read_b128 v[230:233], v221 offset:22528
	ds_read_b128 v[234:237], v221 offset:23552
	global_load_lds_dwordx4 v[238:239], off
	s_add_i32 m0, s33, 0x2000
	s_add_u32 s42, s12, 0x10000
	v_lshl_add_u64 v[240:241], s[12:13], 0, v[160:161]
	s_addc_u32 s43, s13, 0
	s_add_i32 s33, s35, s78
	global_load_lds_dwordx4 v[240:241], off
	v_lshl_add_u64 v[242:243], s[42:43], 0, v[156:157]
	s_mov_b32 m0, s33
	v_lshl_add_u64 v[244:245], s[14:15], 0, v[158:159]
	global_load_lds_dwordx4 v[242:243], off
	v_lshl_add_u64 v[242:243], s[42:43], 0, v[160:161]
	s_add_i32 m0, s33, 0x2000
	s_nop 0
	global_load_lds_dwordx4 v[242:243], off
	v_lshl_add_u64 v[242:243], s[14:15], 0, v[154:155]
	s_mov_b32 m0, s79
	s_nop 0
	global_load_lds_dwordx4 v[242:243], off
	s_mov_b32 m0, s81
	s_nop 0
	global_load_lds_dwordx4 v[244:245], off
	s_waitcnt vmcnt(8)
	s_waitcnt lgkmcnt(0)
	s_barrier
	s_waitcnt lgkmcnt(0)
	v_mfma_f32_16x16x32_bf16 v[68:71], v[0:3], v[190:193], v[68:71]
	v_mfma_f32_16x16x32_bf16 v[64:67], v[138:141], v[190:193], v[64:67]
	v_mfma_f32_16x16x32_bf16 v[52:55], v[0:3], v[198:201], v[52:55]
	v_mfma_f32_16x16x32_bf16 v[48:51], v[138:141], v[198:201], v[48:51]
	v_mfma_f32_16x16x32_bf16 v[36:39], v[0:3], v[222:225], v[36:39]
	v_mfma_f32_16x16x32_bf16 v[32:35], v[138:141], v[222:225], v[32:35]
	v_mfma_f32_16x16x32_bf16 v[0:3], v[0:3], v[230:233], v[20:23]
	v_mfma_f32_16x16x32_bf16 v[68:71], v[4:7], v[194:197], v[68:71]
	v_mfma_f32_16x16x32_bf16 v[64:67], v[142:145], v[194:197], v[64:67]
	v_mfma_f32_16x16x32_bf16 v[52:55], v[4:7], v[202:205], v[52:55]
	v_mfma_f32_16x16x32_bf16 v[48:51], v[142:145], v[202:205], v[48:51]
	v_mfma_f32_16x16x32_bf16 v[36:39], v[4:7], v[226:229], v[36:39]
	v_mfma_f32_16x16x32_bf16 v[32:35], v[142:145], v[226:229], v[32:35]
	v_mfma_f32_16x16x32_bf16 v[0:3], v[4:7], v[234:237], v[0:3]
	v_mfma_f32_16x16x32_bf16 v[4:7], v[138:141], v[230:233], v[16:19]
	v_mfma_f32_16x16x32_bf16 v[4:7], v[142:145], v[234:237], v[4:7]
	v_mfma_f32_16x16x32_bf16 v[16:19], v[146:149], v[190:193], v[60:63]
	v_mfma_f32_16x16x32_bf16 v[60:63], v[150:153], v[194:197], v[16:19]
	v_mfma_f32_16x16x32_bf16 v[16:19], v[182:185], v[190:193], v[56:59]
	v_mfma_f32_16x16x32_bf16 v[56:59], v[186:189], v[194:197], v[16:19]
	v_mfma_f32_16x16x32_bf16 v[16:19], v[146:149], v[198:201], v[44:47]
	v_mfma_f32_16x16x32_bf16 v[44:47], v[150:153], v[202:205], v[16:19]
	v_mfma_f32_16x16x32_bf16 v[16:19], v[182:185], v[198:201], v[40:43]
	v_mfma_f32_16x16x32_bf16 v[40:43], v[186:189], v[202:205], v[16:19]
	v_mfma_f32_16x16x32_bf16 v[16:19], v[146:149], v[222:225], v[28:31]
	v_mfma_f32_16x16x32_bf16 v[28:31], v[150:153], v[226:229], v[16:19]
	v_mfma_f32_16x16x32_bf16 v[16:19], v[182:185], v[222:225], v[24:27]
	v_mfma_f32_16x16x32_bf16 v[12:15], v[146:149], v[230:233], v[12:15]
	v_mfma_f32_16x16x32_bf16 v[8:11], v[182:185], v[230:233], v[8:11]
	v_mfma_f32_16x16x32_bf16 v[24:27], v[186:189], v[226:229], v[16:19]
	v_mfma_f32_16x16x32_bf16 v[12:15], v[150:153], v[234:237], v[12:15]
	v_mfma_f32_16x16x32_bf16 v[8:11], v[186:189], v[234:237], v[8:11]
	s_barrier
	v_add_u32_e32 v96, s67, v165
	s_add_i32 s33, 0, 0x1c000
	ds_read_b128 v[16:19], v96
	ds_read_b128 v[20:23], v96 offset:1024
	ds_read_b128 v[138:141], v96 offset:2048
	ds_read_b128 v[142:145], v96 offset:3072
	v_add_u32_e32 v96, s33, v165
	ds_read_b128 v[146:149], v96
	ds_read_b128 v[150:153], v96 offset:1024
	ds_read_b128 v[182:185], v96 offset:2048
	ds_read_b128 v[186:189], v96 offset:3072
	s_add_u32 s14, s14, 0x40000
	s_addc_u32 s15, s15, 0
	s_mov_b32 m0, s92
	v_lshl_add_u64 v[246:247], s[14:15], 0, v[154:155]
	ds_read_b128 v[190:193], v221 offset:32768
	ds_read_b128 v[194:197], v221 offset:33792
	ds_read_b128 v[198:201], v221 offset:34816
	ds_read_b128 v[202:205], v221 offset:35840
	ds_read_b128 v[222:225], v221 offset:36864
	ds_read_b128 v[226:229], v221 offset:37888
	ds_read_b128 v[230:233], v221 offset:38912
	ds_read_b128 v[234:237], v221 offset:39936
	global_load_lds_dwordx4 v[246:247], off
	v_lshl_add_u64 v[246:247], s[14:15], 0, v[158:159]
	s_mov_b32 m0, s93
	s_nop 0
	global_load_lds_dwordx4 v[246:247], off
	s_waitcnt vmcnt(8)
	s_waitcnt lgkmcnt(0)
	s_barrier
	s_waitcnt lgkmcnt(0)
	v_mfma_f32_16x16x32_bf16 v[134:137], v[16:19], v[190:193], v[134:137]
	v_mfma_f32_16x16x32_bf16 v[130:133], v[138:141], v[190:193], v[130:133]
	v_mfma_f32_16x16x32_bf16 v[118:121], v[16:19], v[198:201], v[118:121]
	v_mfma_f32_16x16x32_bf16 v[114:117], v[138:141], v[198:201], v[114:117]
	v_mfma_f32_16x16x32_bf16 v[102:105], v[16:19], v[222:225], v[102:105]
	v_mfma_f32_16x16x32_bf16 v[98:101], v[138:141], v[222:225], v[98:101]
	v_mfma_f32_16x16x32_bf16 v[84:87], v[16:19], v[230:233], v[84:87]
	v_mfma_f32_16x16x32_bf16 v[80:83], v[138:141], v[230:233], v[80:83]
	v_mfma_f32_16x16x32_bf16 v[134:137], v[20:23], v[194:197], v[134:137]
	v_mfma_f32_16x16x32_bf16 v[130:133], v[142:145], v[194:197], v[130:133]
	v_mfma_f32_16x16x32_bf16 v[118:121], v[20:23], v[202:205], v[118:121]
	v_mfma_f32_16x16x32_bf16 v[114:117], v[142:145], v[202:205], v[114:117]
	v_mfma_f32_16x16x32_bf16 v[102:105], v[20:23], v[226:229], v[102:105]
	v_mfma_f32_16x16x32_bf16 v[98:101], v[142:145], v[226:229], v[98:101]
	v_mfma_f32_16x16x32_bf16 v[84:87], v[20:23], v[234:237], v[84:87]
	v_mfma_f32_16x16x32_bf16 v[80:83], v[142:145], v[234:237], v[80:83]
	v_mfma_f32_16x16x32_bf16 v[126:129], v[146:149], v[190:193], v[126:129]
	v_mfma_f32_16x16x32_bf16 v[122:125], v[182:185], v[190:193], v[122:125]
	v_mfma_f32_16x16x32_bf16 v[110:113], v[146:149], v[198:201], v[110:113]
	v_mfma_f32_16x16x32_bf16 v[106:109], v[182:185], v[198:201], v[106:109]
	v_mfma_f32_16x16x32_bf16 v[92:95], v[146:149], v[222:225], v[92:95]
	v_mfma_f32_16x16x32_bf16 v[88:91], v[182:185], v[222:225], v[88:91]
	v_mfma_f32_16x16x32_bf16 v[76:79], v[146:149], v[230:233], v[76:79]
	v_mfma_f32_16x16x32_bf16 v[72:75], v[182:185], v[230:233], v[72:75]
	v_mfma_f32_16x16x32_bf16 v[126:129], v[150:153], v[194:197], v[126:129]
	v_mfma_f32_16x16x32_bf16 v[122:125], v[186:189], v[194:197], v[122:125]
	v_mfma_f32_16x16x32_bf16 v[110:113], v[150:153], v[202:205], v[110:113]
	v_mfma_f32_16x16x32_bf16 v[106:109], v[186:189], v[202:205], v[106:109]
	v_mfma_f32_16x16x32_bf16 v[92:95], v[150:153], v[226:229], v[92:95]
	v_mfma_f32_16x16x32_bf16 v[88:91], v[186:189], v[226:229], v[88:91]
	v_mfma_f32_16x16x32_bf16 v[76:79], v[150:153], v[234:237], v[76:79]
	v_mfma_f32_16x16x32_bf16 v[72:75], v[186:189], v[234:237], v[72:75]
	s_barrier
	s_add_i32 s14, s67, s78
	v_lshl_add_u64 v[238:239], v[238:239], 0, s[62:63]
	s_mov_b32 m0, s14
	ds_read_b128 v[190:193], v221 offset:49152
	ds_read_b128 v[194:197], v221 offset:50176
	ds_read_b128 v[198:201], v221 offset:51200
	ds_read_b128 v[202:205], v221 offset:52224
	ds_read_b128 v[222:225], v221 offset:53248
	ds_read_b128 v[226:229], v221 offset:54272
	ds_read_b128 v[230:233], v221 offset:55296
	ds_read_b128 v[234:237], v221 offset:56320
	global_load_lds_dwordx4 v[238:239], off
	s_add_i32 m0, s14, 0x2000
	s_add_u32 s12, s12, 0x10080
	v_lshl_add_u64 v[238:239], v[240:241], 0, s[62:63]
	s_addc_u32 s13, s13, 0
	s_add_i32 s14, s33, s78
	global_load_lds_dwordx4 v[238:239], off
	v_lshl_add_u64 v[238:239], s[12:13], 0, v[156:157]
	s_mov_b32 m0, s14
	s_nop 0
	global_load_lds_dwordx4 v[238:239], off
	v_lshl_add_u64 v[238:239], s[12:13], 0, v[160:161]
	s_add_i32 m0, s14, 0x2000
	s_nop 0
	global_load_lds_dwordx4 v[238:239], off
	v_lshl_add_u64 v[238:239], v[242:243], 0, s[62:63]
	s_mov_b32 m0, s21
	s_nop 0
	global_load_lds_dwordx4 v[238:239], off
	v_lshl_add_u64 v[238:239], v[244:245], 0, s[62:63]
	s_mov_b32 m0, s61
	s_nop 0
	global_load_lds_dwordx4 v[238:239], off
	s_waitcnt vmcnt(8)
	s_waitcnt lgkmcnt(0)
	s_barrier
	s_waitcnt lgkmcnt(0)
	v_mfma_f32_16x16x32_bf16 v[68:71], v[16:19], v[190:193], v[68:71]
	v_mfma_f32_16x16x32_bf16 v[52:55], v[16:19], v[198:201], v[52:55]
	v_mfma_f32_16x16x32_bf16 v[36:39], v[16:19], v[222:225], v[36:39]
	v_mfma_f32_16x16x32_bf16 v[0:3], v[16:19], v[230:233], v[0:3]
	v_mfma_f32_16x16x32_bf16 v[68:71], v[20:23], v[194:197], v[68:71]
	v_mfma_f32_16x16x32_bf16 v[64:67], v[138:141], v[190:193], v[64:67]
	v_mfma_f32_16x16x32_bf16 v[52:55], v[20:23], v[202:205], v[52:55]
	v_mfma_f32_16x16x32_bf16 v[48:51], v[138:141], v[198:201], v[48:51]
	v_mfma_f32_16x16x32_bf16 v[36:39], v[20:23], v[226:229], v[36:39]
	v_mfma_f32_16x16x32_bf16 v[32:35], v[138:141], v[222:225], v[32:35]
	v_mfma_f32_16x16x32_bf16 v[20:23], v[20:23], v[234:237], v[0:3]
	v_mfma_f32_16x16x32_bf16 v[0:3], v[138:141], v[230:233], v[4:7]
	v_mfma_f32_16x16x32_bf16 v[64:67], v[142:145], v[194:197], v[64:67]
	v_mfma_f32_16x16x32_bf16 v[48:51], v[142:145], v[202:205], v[48:51]
	v_mfma_f32_16x16x32_bf16 v[32:35], v[142:145], v[226:229], v[32:35]
	v_mfma_f32_16x16x32_bf16 v[16:19], v[142:145], v[234:237], v[0:3]
	v_mfma_f32_16x16x32_bf16 v[0:3], v[146:149], v[190:193], v[60:63]
	v_mfma_f32_16x16x32_bf16 v[60:63], v[150:153], v[194:197], v[0:3]
	v_mfma_f32_16x16x32_bf16 v[0:3], v[182:185], v[190:193], v[56:59]
	v_mfma_f32_16x16x32_bf16 v[56:59], v[186:189], v[194:197], v[0:3]
	v_mfma_f32_16x16x32_bf16 v[0:3], v[146:149], v[198:201], v[44:47]
	v_mfma_f32_16x16x32_bf16 v[44:47], v[150:153], v[202:205], v[0:3]
	v_mfma_f32_16x16x32_bf16 v[0:3], v[182:185], v[198:201], v[40:43]
	v_mfma_f32_16x16x32_bf16 v[40:43], v[186:189], v[202:205], v[0:3]
	v_mfma_f32_16x16x32_bf16 v[0:3], v[146:149], v[222:225], v[28:31]
	v_mfma_f32_16x16x32_bf16 v[28:31], v[150:153], v[226:229], v[0:3]
	v_mfma_f32_16x16x32_bf16 v[0:3], v[182:185], v[222:225], v[24:27]
	v_mfma_f32_16x16x32_bf16 v[24:27], v[186:189], v[226:229], v[0:3]
	v_mfma_f32_16x16x32_bf16 v[0:3], v[146:149], v[230:233], v[12:15]
	v_mfma_f32_16x16x32_bf16 v[12:15], v[150:153], v[234:237], v[0:3]
	v_mfma_f32_16x16x32_bf16 v[0:3], v[182:185], v[230:233], v[8:11]
	v_mfma_f32_16x16x32_bf16 v[8:11], v[186:189], v[234:237], v[0:3]
	s_barrier
	s_add_i32 s27, s27, 2
	s_add_u32 s4, s4, 0x100
	s_addc_u32 s5, s5, 0
	s_add_u32 s19, s19, 0x100
	s_addc_u32 s26, s26, 0
	s_cmp_gt_u32 s27, 13
	s_cbranch_scc0 .LBB0_750
	v_readlane_b32 s4, v252, 30
	v_readlane_b32 s5, v252, 31
	s_and_b64 vcc, exec, s[4:5]
	s_cbranch_vccz .LBB0_753
	s_barrier
